# ret context units moved to next phase on idle workgroups + f32->f16 weight conversion rebalanced and moved into the idle tail of the FFN-up GEMM phases
# speedup vs baseline: 1.0046x; 1.0031x over previous
.Lretctx_resume:
	v_readlane_b32 s0, v253, 17
	v_readlane_b32 s1, v253, 18
	s_andn2_b64 vcc, exec, s[0:1]
	s_cbranch_vccnz .LBB0_924
	s_load_dword s0, s[64:65], 0x0
	v_readlane_b32 s1, v251, 36
	s_mov_b32 s2, s91
	s_waitcnt lgkmcnt(0)
	s_cmp_gt_u32 s0, 16
	s_waitcnt vmcnt(0)
	v_lshl_add_u32 v0, s1, 6, v220
	s_cselect_b32 s1, 8, 0
	s_cmp_lt_i32 s2, s1
	s_cbranch_scc1 .LBB0_923
.LBB0_923:
	s_barrier

.LBB0_963:
	v_readlane_b32 s0, v254, 9
	v_readlane_b32 s1, v254, 10
	s_andn2_b64 vcc, exec, s[0:1]
	s_cbranch_vccnz .LBB0_1032
	v_readlane_b32 s1, v251, 36
	s_waitcnt lgkmcnt(0)
	s_cmp_gt_u32 s26, 16
	s_cselect_b32 s0, 8, 0
	v_lshl_add_u32 v0, s1, 6, v220
	s_mov_b32 s1, s91
	s_cmp_lt_i32 s1, s0
	s_cbranch_scc1 .LBB0_1032
.LBB0_1032:
	v_readlane_b32 s14, v252, 47
	v_readlane_b32 s15, v252, 48

.LBB0_1280:
	v_readlane_b32 s4, v252, 47
	v_readlane_b32 s5, v252, 48
	s_barrier
	v_readlane_b32 s3, v252, 46
	v_readlane_b32 s12, v255, 45
	s_cmp_lt_u32 s3, 150
	s_cbranch_scc1 .Lcvtg_skip
	s_cmp_gt_u32 s12, 2
	s_cbranch_scc1 .Lcvtg_skip
	s_add_i32 s12, s12, 1
	v_readlane_b32 s4, v251, 36
	v_readlane_b32 s5, v254, 25
	s_sub_i32 s0, s3, 150
	s_lshl_b32 s0, s0, 3
	s_add_i32 s0, s0, s4
	s_mul_i32 s15, s4, 0x2100
	s_mov_b32 s1, 848
	s_cmp_lg_u32 s5, 0
	s_movk_i32 s14, 0x3800
	s_cselect_b32 s14, 7168, s14
	s_cselect_b32 s3, 0, 7168
	s_add_i32 s0, s0, s3
.Lcvtg_entry:
	v_lshrrev_b32_e32 v100, 3, v220
	v_and_b32_e32 v101, 7, v220
	v_mul_u32_u24_e32 v102, 0x84, v100
	v_lshl_add_u32 v102, v101, 4, v102
	v_add_u32_e32 v102, s15, v102
	v_mul_u32_u24_e32 v103, 0x420, v101
	v_lshl_add_u32 v103, v100, 2, v103
	v_add_u32_e32 v103, s15, v103
	v_and_b32_e32 v104, 3, v100
	v_lshrrev_b32_e32 v105, 2, v100
	v_lshl_or_b32 v104, v105, 4, v104
	v_lshlrev_b32_e32 v105, 4, v101
.Lcvtg_loop:
	s_cmp_ge_u32 s0, s14
	s_cbranch_scc1 .Lcvtg_done2
	s_cmp_lt_u32 s0, 2816
	s_cbranch_scc1 .Lcvtg_job0
	s_cmp_lt_u32 s0, 4224
	s_cbranch_scc1 .Lcvtg_job1
	s_cmp_lt_u32 s0, 4992
	s_cbranch_scc1 .Lcvtg_job2
	s_cmp_lt_u32 s0, 5248
	s_cbranch_scc1 .Lcvtg_job3
	s_cmp_lt_u32 s0, 5504
	s_cbranch_scc1 .Lcvtg_job4
	s_cmp_lt_u32 s0, 6528
	s_cbranch_scc1 .Lcvtg_job5
	s_cmp_lt_u32 s0, 7552
	s_cbranch_scc1 .Lcvtg_job6
	s_cmp_lt_u32 s0, 8576
	s_cbranch_scc1 .Lcvtg_job7
	s_cmp_lt_u32 s0, 9088
	s_cbranch_scc1 .Lcvtg_job8
	s_cmp_lt_u32 s0, 9600
	s_cbranch_scc1 .Lcvtg_job9
	s_cmp_lt_u32 s0, 10112
	s_cbranch_scc1 .Lcvtg_job10
	s_cmp_lt_u32 s0, 12928
	s_cbranch_scc1 .Lcvtg_job11
	s_branch .Lcvtg_job12
.Lcvtg_job0:
	s_mov_b32 s10, s0
	v_readlane_b32 s4, v251, 14
	v_readlane_b32 s5, v251, 15
	s_mul_i32 s3, s12, 0x1600000
	s_mov_b32 s8, 22528
	s_mov_b32 s13, 0
	s_mov_b32 s9, 2048
	s_mov_b32 s2, 1
	s_mov_b32 s11, 0
	s_mul_i32 vcc_lo, s10, 5958
	s_lshr_b32 vcc_lo, vcc_lo, 20
	s_mul_i32 vcc_hi, vcc_lo, 176
	s_sub_i32 s10, s10, vcc_hi
	s_branch .Lcvtg_common
.Lcvtg_job1:
	s_sub_i32 s10, s0, 2816
	v_readlane_b32 s4, v251, 16
	v_readlane_b32 s5, v251, 17
	s_mul_i32 s3, s12, 0xb00000
	s_mov_b32 s8, 4096
	s_mov_b32 s13, 0
	s_mov_b32 s9, 5632
	s_mov_b32 s2, 3
	s_mov_b32 s11, 11534336
	s_lshr_b32 vcc_lo, s10, 5
	s_and_b32 s10, s10, 31
	s_branch .Lcvtg_common
.Lcvtg_job2:
	s_sub_i32 s10, s0, 4224
	v_readlane_b32 s4, v251, 18
	v_readlane_b32 s5, v251, 19
	s_mul_i32 s3, s12, 0x2000000
	s_mov_b32 s8, 32768
	s_mov_b32 s13, 0
	s_mov_b32 s9, 2048
	s_mov_b32 s2, 0
	s_mov_b32 s11, 17301504
	s_mul_i32 vcc_lo, s10, 1366
	s_lshr_b32 vcc_lo, vcc_lo, 16
	s_mul_i32 vcc_hi, vcc_lo, 48
	s_sub_i32 s10, s10, vcc_hi
	s_branch .Lcvtg_common
.Lcvtg_job3:
	s_sub_i32 s10, s0, 4992
	v_readlane_b32 s4, v251, 18
	v_readlane_b32 s5, v251, 19
	s_mul_i32 s3, s12, 0x2000000
	s_mov_b32 s8, 32768
	s_mov_b32 s13, 0
	s_mov_b32 s9, 2048
	s_mov_b32 s2, 2
	s_mov_b32 s11, 20447232
	s_lshr_b32 vcc_lo, s10, 4
	s_and_b32 s10, s10, 15
	s_branch .Lcvtg_common
.Lcvtg_job4:
	s_sub_i32 s10, s0, 5248
	v_readlane_b32 s4, v251, 18
	v_readlane_b32 s5, v251, 19
	s_mul_i32 s3, s12, 0x2000000
	s_mov_b32 s8, 32768
	s_mov_b32 s13, 6144
	s_mov_b32 s9, 2048
	s_mov_b32 s2, 2
	s_mov_b32 s11, 21495808
	s_lshr_b32 vcc_lo, s10, 4
	s_and_b32 s10, s10, 15
	s_branch .Lcvtg_common
.Lcvtg_job5:
	s_sub_i32 s10, s0, 5504
	v_readlane_b32 s4, v251, 18
	v_readlane_b32 s5, v251, 19
	s_mul_i32 s3, s12, 0x2000000
	s_mov_b32 s8, 32768
	s_mov_b32 s13, 8192
	s_mov_b32 s9, 2048
	s_mov_b32 s2, 3
	s_mov_b32 s11, 22544384
	s_lshr_b32 vcc_lo, s10, 6
	s_and_b32 s10, s10, 63
	s_branch .Lcvtg_common
.Lcvtg_job6:
	s_sub_i32 s10, s0, 6528
	v_readlane_b32 s4, v251, 18
	v_readlane_b32 s5, v251, 19
	s_mul_i32 s3, s12, 0x2000000
	s_mov_b32 s8, 32768
	s_mov_b32 s13, 16384
	s_mov_b32 s9, 2048
	s_mov_b32 s2, 4
	s_mov_b32 s11, 26738688
	s_lshr_b32 vcc_lo, s10, 6
	s_and_b32 s10, s10, 63
	s_branch .Lcvtg_common
.Lcvtg_job7:
	s_sub_i32 s10, s0, 7552
	v_readlane_b32 s4, v251, 18
	v_readlane_b32 s5, v251, 19
	s_mul_i32 s3, s12, 0x2000000
	s_mov_b32 s8, 32768
	s_mov_b32 s13, 24576
	s_mov_b32 s9, 2048
	s_mov_b32 s2, 3
	s_mov_b32 s11, 30932992
	s_lshr_b32 vcc_lo, s10, 6
	s_and_b32 s10, s10, 63
	s_branch .Lcvtg_common
.Lcvtg_job8:
	s_sub_i32 s10, s0, 8576
	v_readlane_b32 s4, v251, 24
	v_readlane_b32 s5, v251, 25
	s_mul_i32 s3, s12, 0x400000
	s_mov_b32 s8, 4096
	s_mov_b32 s13, 0
	s_mov_b32 s9, 2048
	s_mov_b32 s2, 3
	s_mov_b32 s11, 35127296
	s_lshr_b32 vcc_lo, s10, 5
	s_and_b32 s10, s10, 31
	s_branch .Lcvtg_common
.Lcvtg_job9:
	s_sub_i32 s10, s0, 9088
	v_readlane_b32 s4, v251, 26
	v_readlane_b32 s5, v251, 27
	s_mul_i32 s3, s12, 0x400000
	s_mov_b32 s8, 4096
	s_mov_b32 s13, 0
	s_mov_b32 s9, 2048
	s_mov_b32 s2, 3
	s_mov_b32 s11, 37224448
	s_lshr_b32 vcc_lo, s10, 5
	s_and_b32 s10, s10, 31
	s_branch .Lcvtg_common
.Lcvtg_job10:
	s_sub_i32 s10, s0, 9600
	v_readlane_b32 s4, v251, 28
	v_readlane_b32 s5, v251, 29
	s_mul_i32 s3, s12, 0x400000
	s_mov_b32 s8, 4096
	s_mov_b32 s13, 0
	s_mov_b32 s9, 2048
	s_mov_b32 s2, 3
	s_mov_b32 s11, 39321600
	s_lshr_b32 vcc_lo, s10, 5
	s_and_b32 s10, s10, 31
	s_branch .Lcvtg_common
.Lcvtg_job11:
	s_sub_i32 s10, s0, 10112
	v_readlane_b32 s4, v251, 30
	v_readlane_b32 s5, v251, 31
	s_mul_i32 s3, s12, 0x1600000
	s_mov_b32 s8, 22528
	s_mov_b32 s13, 0
	s_mov_b32 s9, 2048
	s_mov_b32 s2, 1
	s_mov_b32 s11, 41418752
	s_mul_i32 vcc_lo, s10, 5958
	s_lshr_b32 vcc_lo, vcc_lo, 20
	s_mul_i32 vcc_hi, vcc_lo, 176
	s_sub_i32 s10, s10, vcc_hi
	s_branch .Lcvtg_common
.Lcvtg_job12:
	s_sub_i32 s10, s0, 12928
	v_readlane_b32 s4, v252, 26
	v_readlane_b32 s5, v252, 27
	s_mul_i32 s3, s12, 0xb00000
	s_mov_b32 s8, 4096
	s_mov_b32 s13, 0
	s_mov_b32 s9, 5632
	s_mov_b32 s2, 3
	s_mov_b32 s11, 52953088
	s_lshr_b32 vcc_lo, s10, 5
	s_and_b32 s10, s10, 31
	s_branch .Lcvtg_common
.Lcvtg_common:
	s_add_u32 s4, s4, s3
	s_addc_u32 s5, s5, 0
	s_lshl_b32 s3, vcc_lo, 6
	s_mul_i32 vcc_hi, s3, s8
	s_add_u32 s4, s4, vcc_hi
	s_addc_u32 s5, s5, 0
	s_lshl_b32 s10, s10, 5
	s_lshl_b32 vcc_hi, s10, 2
	s_add_i32 s13, s13, vcc_hi
	s_add_u32 s4, s4, s13
	s_addc_u32 s5, s5, 0
	v_readlane_b32 s6, v251, 41
	v_readlane_b32 s7, v251, 42
	s_and_b32 s13, s12, 1
	s_mul_i32 s13, s13, 0x3800000
	s_add_i32 s11, s11, s13
	s_lshl_b32 s13, s3, 1
	s_add_i32 s11, s11, s13
	s_add_u32 s6, s6, s11
	s_addc_u32 s7, s7, 0
	s_cmp_eq_u32 s2, 1
	s_cbranch_scc1 .Lcvtg_u1
	s_cmp_eq_u32 s2, 2
	s_cbranch_scc1 .Lcvtg_u2
	s_cmp_eq_u32 s2, 4
	s_cbranch_scc1 .Lcvtg_u4
	s_mov_b32 s11, s10
	s_branch .Lcvtg_ud
.Lcvtg_u1:
	s_cmp_ge_u32 s10, 2816
	s_cselect_b32 s3, 1, 0
	s_mul_i32 s13, s3, 2816
	s_sub_i32 s13, s10, s13
	s_lshr_b32 s11, s13, 7
	s_lshl_b32 s11, s11, 8
	s_lshl_b32 s3, s3, 7
	s_add_i32 s11, s11, s3
	s_and_b32 s13, s13, 96
	s_add_i32 s11, s11, s13
	s_branch .Lcvtg_ud
.Lcvtg_u2:
	s_and_b32 s11, s10, 0xffffff80
	s_bfe_u32 s3, s10, 0x10006
	s_lshl_b32 s3, s3, 6
	s_add_i32 s11, s11, s3
	s_bfe_u32 s3, s10, 0x10005
	s_lshl_b32 s3, s3, 4
	s_add_i32 s11, s11, s3
	s_branch .Lcvtg_ud
.Lcvtg_u4:
	s_lshr_b32 s3, s10, 10
	s_and_b32 s13, s10, 1023
	s_lshr_b32 s11, s13, 7
	s_lshl_b32 s11, s11, 8
	s_lshl_b32 s3, s3, 7
	s_add_i32 s11, s11, s3
	s_and_b32 s13, s13, 96
	s_add_i32 s11, s11, s13
.Lcvtg_ud:
	s_mul_i32 s11, s11, s9
	s_add_u32 s6, s6, s11
	s_addc_u32 s7, s7, 0
	v_mad_u32_u24 v0, v100, s8, v105
	s_lshl_b32 s13, s8, 3
	global_load_dwordx4 v[8:11], v0, s[4:5]
	s_add_u32 s4, s4, s13
	s_addc_u32 s5, s5, 0
	s_nop 0
	global_load_dwordx4 v[12:15], v0, s[4:5]
	s_add_u32 s4, s4, s13
	s_addc_u32 s5, s5, 0
	s_nop 0
	global_load_dwordx4 v[16:19], v0, s[4:5]
	s_add_u32 s4, s4, s13
	s_addc_u32 s5, s5, 0
	s_nop 0
	global_load_dwordx4 v[20:23], v0, s[4:5]
	s_add_u32 s4, s4, s13
	s_addc_u32 s5, s5, 0
	s_nop 0
	global_load_dwordx4 v[24:27], v0, s[4:5]
	s_add_u32 s4, s4, s13
	s_addc_u32 s5, s5, 0
	s_nop 0
	global_load_dwordx4 v[28:31], v0, s[4:5]
	s_add_u32 s4, s4, s13
	s_addc_u32 s5, s5, 0
	s_nop 0
	global_load_dwordx4 v[34:37], v0, s[4:5]
	s_add_u32 s4, s4, s13
	s_addc_u32 s5, s5, 0
	s_nop 0
	global_load_dwordx4 v[38:41], v0, s[4:5]
	v_mov_b32_e32 v1, v104
	s_lshl_b32 s3, s9, 2
	s_mov_b32 s11, s3
	s_mov_b32 s13, s3
	s_cmp_eq_u32 s2, 0
	s_cbranch_scc0 .Lcvtg_k0n
	v_mov_b32_e32 v1, v100
	s_lshl_b32 s3, s9, 3
	s_mov_b32 s11, s3
	s_mov_b32 s13, s3
.Lcvtg_k0n:
	s_cmp_eq_u32 s2, 2
	s_cbranch_scc0 .Lcvtg_k2n
	v_mov_b32_e32 v1, v100
	s_lshl_b32 s3, s9, 3
	s_mul_i32 s11, s9, 24
	s_mov_b32 s13, s3
.Lcvtg_k2n:
	v_mul_u32_u24_e32 v1, s9, v1
	v_add_u32_e32 v1, v105, v1
	s_waitcnt vmcnt(0)
	ds_write_b32 v102, v8
	ds_write_b32 v102, v9 offset:4
	ds_write_b32 v102, v10 offset:8
	ds_write_b32 v102, v11 offset:12
	ds_write_b32 v102, v12 offset:1056
	ds_write_b32 v102, v13 offset:1060
	ds_write_b32 v102, v14 offset:1064
	ds_write_b32 v102, v15 offset:1068
	ds_write_b32 v102, v16 offset:2112
	ds_write_b32 v102, v17 offset:2116
	ds_write_b32 v102, v18 offset:2120
	ds_write_b32 v102, v19 offset:2124
	ds_write_b32 v102, v20 offset:3168
	ds_write_b32 v102, v21 offset:3172
	ds_write_b32 v102, v22 offset:3176
	ds_write_b32 v102, v23 offset:3180
	ds_write_b32 v102, v24 offset:4224
	ds_write_b32 v102, v25 offset:4228
	ds_write_b32 v102, v26 offset:4232
	ds_write_b32 v102, v27 offset:4236
	ds_write_b32 v102, v28 offset:5280
	ds_write_b32 v102, v29 offset:5284
	ds_write_b32 v102, v30 offset:5288
	ds_write_b32 v102, v31 offset:5292
	ds_write_b32 v102, v34 offset:6336
	ds_write_b32 v102, v35 offset:6340
	ds_write_b32 v102, v36 offset:6344
	ds_write_b32 v102, v37 offset:6348
	ds_write_b32 v102, v38 offset:7392
	ds_write_b32 v102, v39 offset:7396
	ds_write_b32 v102, v40 offset:7400
	ds_write_b32 v102, v41 offset:7404
	s_waitcnt lgkmcnt(0)
	ds_read2_b32 v[42:43], v103 offset0:0 offset1:33
	ds_read2_b32 v[44:45], v103 offset0:66 offset1:99
	ds_read2_b32 v[46:47], v103 offset0:132 offset1:165
	ds_read2_b32 v[48:49], v103 offset0:198 offset1:231
	ds_read2_b32 v[50:51], v103 offset0:8 offset1:41
	ds_read2_b32 v[52:53], v103 offset0:74 offset1:107
	ds_read2_b32 v[54:55], v103 offset0:140 offset1:173
	ds_read2_b32 v[56:57], v103 offset0:206 offset1:239
	ds_read2_b32 v[58:59], v103 offset0:16 offset1:49
	ds_read2_b32 v[60:61], v103 offset0:82 offset1:115
	ds_read2_b32 v[62:63], v103 offset0:148 offset1:181
	ds_read2_b32 v[64:65], v103 offset0:214 offset1:247
	ds_read2_b32 v[66:67], v103 offset0:24 offset1:57
	ds_read2_b32 v[68:69], v103 offset0:90 offset1:123
	ds_read2_b32 v[70:71], v103 offset0:156 offset1:189
	ds_read2_b32 v[72:73], v103 offset0:222 offset1:255
	s_waitcnt lgkmcnt(0)
	v_cvt_pk_f16_f32 v74, v42, v43
	v_cvt_pk_f16_f32 v75, v44, v45
	v_cvt_pk_f16_f32 v76, v46, v47
	v_cvt_pk_f16_f32 v77, v48, v49
	v_cvt_pk_f16_f32 v78, v50, v51
	v_cvt_pk_f16_f32 v79, v52, v53
	v_cvt_pk_f16_f32 v80, v54, v55
	v_cvt_pk_f16_f32 v81, v56, v57
	v_cvt_pk_f16_f32 v82, v58, v59
	v_cvt_pk_f16_f32 v83, v60, v61
	v_cvt_pk_f16_f32 v84, v62, v63
	v_cvt_pk_f16_f32 v85, v64, v65
	v_cvt_pk_f16_f32 v86, v66, v67
	v_cvt_pk_f16_f32 v87, v68, v69
	v_cvt_pk_f16_f32 v88, v70, v71
	v_cvt_pk_f16_f32 v89, v72, v73
	global_store_dwordx4 v1, v[74:77], s[6:7]
	s_add_u32 s6, s6, s3
	s_addc_u32 s7, s7, 0
	s_nop 0
	global_store_dwordx4 v1, v[78:81], s[6:7]
	s_add_u32 s6, s6, s11
	s_addc_u32 s7, s7, 0
	s_nop 0
	global_store_dwordx4 v1, v[82:85], s[6:7]
	s_add_u32 s6, s6, s13
	s_addc_u32 s7, s7, 0
	s_nop 0
	global_store_dwordx4 v1, v[86:89], s[6:7]
	s_add_i32 s0, s0, s1
	s_branch .Lcvtg_loop
.Lcvtg_done2:
.Lcvtg_skip:
	v_readlane_b32 s4, v252, 47
	v_readlane_b32 s5, v252, 48
